# G3: the item's gate rows (8 loads) requested at item start; output stage no longer waits on memory (next item's state prefetch stays in flight)
# speedup vs baseline: 1.0044x; 1.0006x over previous
; __device__ __forceinline__ unsigned cvt_pk_bf16(float lo, float hi) { unsigned r; asm volatile("v_cvt_pk_bf16_f32 %0, %1, %2" : "=v"(r) : "v"(lo), "v"(hi)); return r; }
; __device__ __forceinline__ float bf_lo(unsigned w) { return __uint_as_float(w << 16); }
; __device__ __forceinline__ float bf_hi(unsigned w) { return __uint_as_float(w & 0xffff0000u); }
; __device__ __forceinline__ float siluf_(float x) { return x * sigmoidf_(x); }
; __device__ __forceinline__ void gla_g3(const Params& P, unsigned char* lds) {
;     ...
;         u32x2 gwp[4][2];
; #pragma unroll
;         for (int lt = 0; lt < 4; ++lt)
; #pragma unroll
;             for (int nt = 0; nt < 2; ++nt) { const int l = 16 * lt + fr, lc = l < I.L ? l : I.L - 1;
;                 gwp[lt][nt] = *(const u32x2*)(gg + (size_t)(I.row0 + lc) * D + I.h * DV + 32 * wid + 16 * nt + 4 * fq); }
;         __syncthreads();
; #pragma unroll
;         for (int lt = 0; lt < 4; ++lt) { const int l = 16 * lt + fr;
;             if (l < I.L) { float tot = 0.f;
; #pragma unroll
;                 for (int w8 = 0; w8 < 8; ++w8) tot += ssh[w8 * 64 + l];
;                 const float ro = rsqrtf(tot * (1.0f / 256.0f) + EPS);
; #pragma unroll
;                 for (int nt = 0; nt < 2; ++nt) { const int dvh = 32 * wid + 16 * nt + 4 * fq; const size_t off = (size_t)(I.row0 + l) * D + I.h * DV + dvh;
;                     const u32x2 gw = gwp[lt][nt]; const f32x4 nw = *(const f32x4*)(P.in[16] + dvh);
;                     const float o0 = acc[nt][lt][0] * ro * nw[0] * siluf_(bf_lo(gw.x)), o1 = acc[nt][lt][1] * ro * nw[1] * siluf_(bf_hi(gw.x));
;                     const float o2 = acc[nt][lt][2] * ro * nw[2] * siluf_(bf_lo(gw.y)), o3 = acc[nt][lt][3] * ro * nw[3] * siluf_(bf_hi(gw.y));
;                     u32x2 w; w.x = cvt_pk_bf16(o0, o1); w.y = cvt_pk_bf16(o2, o3); *(u32x2*)(og + off) = w; } } }
.LBB0_2170:
	s_or_b64 exec, exec, s[62:63]
	v_min_i32_e32 v64, s64, v103
	v_add_u32_e32 v92, s60, v64
	v_min_i32_e32 v64, s64, v132
	s_lshl_b32 s46, s46, 1
	v_ashrrev_i32_e32 v93, 31, v92
	v_add_u32_e32 v94, s60, v64
	v_lshl_add_u64 v[90:91], v[74:75], 0, s[46:47]
	v_lshlrev_b64 v[92:93], 11, v[92:93]
	v_ashrrev_i32_e32 v95, 31, v94
	v_lshl_add_u64 v[92:93], v[90:91], 0, v[92:93]
	v_lshlrev_b64 v[94:95], 11, v[94:95]
	v_min_i32_e32 v64, s64, v133
	v_lshl_add_u64 v[94:95], v[90:91], 0, v[94:95]
	v_mov_b32_e32 v178, v228
	v_mov_b32_e32 v179, v229
	v_mov_b32_e32 v180, v230
	v_mov_b32_e32 v181, v231
	v_mov_b32_e32 v100, v232
	v_mov_b32_e32 v101, v233
	v_mov_b32_e32 v98, v234
	v_mov_b32_e32 v99, v235
	v_add_u32_e32 v92, s60, v64
	v_min_i32_e32 v64, s64, v134
	v_add_u32_e32 v94, s60, v64
	v_ashrrev_i32_e32 v93, 31, v92
	v_ashrrev_i32_e32 v95, 31, v94
	v_lshlrev_b64 v[92:93], 11, v[92:93]
	v_lshlrev_b64 v[94:95], 11, v[94:95]
	v_lshl_add_u64 v[92:93], v[90:91], 0, v[92:93]
	v_lshl_add_u64 v[90:91], v[90:91], 0, v[94:95]
	v_mov_b32_e32 v96, v236
	v_mov_b32_e32 v97, v237
	v_mov_b32_e32 v94, v238
	v_mov_b32_e32 v95, v239
	s_nop 0
	v_mov_b32_e32 v92, v244
	v_mov_b32_e32 v93, v245
	s_nop 0
	v_mov_b32_e32 v90, v246
	v_mov_b32_e32 v91, v247
	s_waitcnt lgkmcnt(0)
	s_barrier
	s_nop 0
	v_mov_b32_e32 v174, v212
	v_mov_b32_e32 v175, v213
	v_mov_b32_e32 v176, v214
	v_mov_b32_e32 v177, v215
	ds_read2st64_b32 v[184:185], v104 offset1:1
	ds_read2st64_b32 v[186:187], v104 offset0:2 offset1:3
	ds_read2st64_b32 v[188:189], v104 offset0:4 offset1:5
	ds_read2st64_b32 v[190:191], v104 offset0:6 offset1:7
	v_add_u32_e32 v182, s60, v103
	s_add_u32 s62, s79, s46
	v_ashrrev_i32_e32 v183, 31, v182
	s_waitcnt lgkmcnt(3)
	v_add_f32_e32 v64, 0, v184
	v_add_f32_e32 v64, v64, v185
	s_waitcnt lgkmcnt(2)
	v_add_f32_e32 v64, v64, v186
	v_add_f32_e32 v64, v64, v187
	s_waitcnt lgkmcnt(1)
	v_add_f32_e32 v64, v64, v188
	v_add_f32_e32 v64, v64, v189
	s_waitcnt lgkmcnt(0)
	v_add_f32_e32 v64, v64, v190
	v_add_f32_e32 v64, v64, v191
	v_fmamk_f32 v64, v64, 0x3b800000, v169
	v_mul_f32_e32 v173, 0x4b800000, v64
	v_cmp_gt_f32_e32 vcc, s90, v64
	s_addc_u32 s63, s80, 0
	v_lshlrev_b64 v[182:183], 11, v[182:183]
	v_cndmask_b32_e32 v64, v64, v173, vcc
	v_rsq_f32_e32 v64, v64
	v_mov_b32_e32 v89, v65
	v_lshl_add_u64 v[182:183], s[62:63], 0, v[182:183]
	v_lshl_add_u64 v[182:183], v[182:183], 0, v[88:89]
	v_mul_f32_e32 v173, 0x45800000, v64
	v_cndmask_b32_e32 v64, v64, v173, vcc
	v_mul_f32_e32 v185, v60, v64
	v_mul_f32_e32 v187, v62, v64
	v_mul_f32_e32 v61, v61, v64
	v_mul_f32_e32 v63, v63, v64
	v_mul_f32_e32 v57, v57, v64
	v_mul_f32_e32 v59, v59, v64
	v_cmp_gt_u32_e32 vcc, s95, v132
	s_nop 0
	v_and_b32_e32 v60, 0xffff0000, v178
	v_lshlrev_b32_e32 v186, 16, v179
	v_lshlrev_b32_e32 v184, 16, v178
	v_and_b32_e32 v62, 0xffff0000, v179
	v_mul_f32_e32 v173, 0xbfb8aa3b, v184
	v_mul_f32_e32 v178, 0xbfb8aa3b, v62
	v_exp_f32_e32 v173, v173
	v_exp_f32_e32 v178, v178
	v_add_f32_e32 v173, 1.0, v173
	v_add_f32_e32 v178, 1.0, v178
	v_rcp_f32_e32 v188, v173
	s_nop 0
	v_mov_b32_e32 v189, v174
	v_mov_b32_e32 v191, v176
	v_mul_f32_e32 v174, 0xbfb8aa3b, v60
	v_mul_f32_e32 v176, 0xbfb8aa3b, v186
	v_exp_f32_e32 v174, v174
	v_exp_f32_e32 v176, v176
	v_add_f32_e32 v174, 1.0, v174
	v_add_f32_e32 v176, 1.0, v176
	v_rcp_f32_e32 v174, v174
	v_rcp_f32_e32 v190, v176
	v_rcp_f32_e32 v176, v178
	v_pk_mul_f32 v[178:179], v[188:189], v[184:185]
	v_pk_mul_f32 v[60:61], v[174:175], v[60:61]
	v_pk_mul_f32 v[174:175], v[190:191], v[186:187]
	v_pk_mul_f32 v[62:63], v[176:177], v[62:63]
	v_mul_f32_e32 v60, v60, v61
	v_mul_f32_e32 v61, v174, v175
	v_mul_f32_e32 v173, v178, v179
	v_mul_f32_e32 v62, v62, v63
	v_cvt_pk_bf16_f32 v60, v173, v60
	v_cvt_pk_bf16_f32 v61, v61, v62
	global_store_dwordx2 v[182:183], v[60:61], off
	s_nop 0
	v_mov_b32_e32 v60, v216
	v_mov_b32_e32 v61, v217
	v_mov_b32_e32 v62, v218
	v_mov_b32_e32 v63, v219
	v_mul_f32_e32 v175, v56, v64
	v_mul_f32_e32 v177, v58, v64
	v_and_b32_e32 v56, 0xffff0000, v180
	v_and_b32_e32 v58, 0xffff0000, v181
	v_lshlrev_b32_e32 v174, 16, v180
	v_lshlrev_b32_e32 v176, 16, v181
	v_mul_f32_e32 v173, 0xbfb8aa3b, v56
	v_mul_f32_e32 v179, 0xbfb8aa3b, v58
	v_mul_f32_e32 v64, 0xbfb8aa3b, v174
	v_mul_f32_e32 v178, 0xbfb8aa3b, v176
	v_exp_f32_e32 v173, v173
	v_exp_f32_e32 v179, v179
	v_exp_f32_e32 v64, v64
	v_exp_f32_e32 v178, v178
	v_add_f32_e32 v173, 1.0, v173
	v_add_f32_e32 v184, 1.0, v179
	v_add_f32_e32 v64, 1.0, v64
	v_add_f32_e32 v180, 1.0, v178
	v_rcp_f32_e32 v178, v64
	v_rcp_f32_e32 v180, v180
	s_nop 0
	v_mov_b32_e32 v179, v60
	v_rcp_f32_e32 v60, v173
	v_mov_b32_e32 v181, v62
	v_rcp_f32_e32 v62, v184
	v_pk_mul_f32 v[174:175], v[178:179], v[174:175]
	v_pk_mul_f32 v[56:57], v[60:61], v[56:57]
	v_pk_mul_f32 v[176:177], v[180:181], v[176:177]
	v_pk_mul_f32 v[58:59], v[62:63], v[58:59]
	v_mul_f32_e32 v56, v56, v57
	v_mul_f32_e32 v57, v58, v59
	v_mul_f32_e32 v64, v174, v175
	v_mul_f32_e32 v173, v176, v177
	v_cvt_pk_bf16_f32 v56, v64, v56
	v_cvt_pk_bf16_f32 v57, v173, v57
	global_store_dwordx2 v[182:183], v[56:57], off offset:32
	s_and_saveexec_b64 s[76:77], vcc
	s_cbranch_execz .LBB0_2177
; __device__ __forceinline__ unsigned cvt_pk_bf16(float lo, float hi) { unsigned r; asm volatile("v_cvt_pk_bf16_f32 %0, %1, %2" : "=v"(r) : "v"(lo), "v"(hi)); return r; }
; __device__ __forceinline__ float bf_lo(unsigned w) { return __uint_as_float(w << 16); }
; __device__ __forceinline__ float bf_hi(unsigned w) { return __uint_as_float(w & 0xffff0000u); }
; __device__ __forceinline__ float siluf_(float x) { return x * sigmoidf_(x); }
; __device__ __forceinline__ void gla_g3(const Params& P, unsigned char* lds) {
;     ...
;         __syncthreads();
; #pragma unroll
;         for (int lt = 0; lt < 4; ++lt) { const int l = 16 * lt + fr;
;             if (l < I.L) { float tot = 0.f;
; #pragma unroll
;                 for (int w8 = 0; w8 < 8; ++w8) tot += ssh[w8 * 64 + l];
;                 const float ro = rsqrtf(tot * (1.0f / 256.0f) + EPS);
; #pragma unroll
;                 for (int nt = 0; nt < 2; ++nt) { const int dvh = 32 * wid + 16 * nt + 4 * fq; const size_t off = (size_t)(I.row0 + l) * D + I.h * DV + dvh;
;                     const u32x2 gw = gwp[lt][nt]; const f32x4 nw = *(const f32x4*)(P.in[16] + dvh);
;                     const float o0 = acc[nt][lt][0] * ro * nw[0] * siluf_(bf_lo(gw.x)), o1 = acc[nt][lt][1] * ro * nw[1] * siluf_(bf_hi(gw.x));
;                     const float o2 = acc[nt][lt][2] * ro * nw[2] * siluf_(bf_lo(gw.y)), o3 = acc[nt][lt][3] * ro * nw[3] * siluf_(bf_hi(gw.y));
;                     u32x2 w; w.x = cvt_pk_bf16(o0, o1); w.y = cvt_pk_bf16(o2, o3); *(u32x2*)(og + off) = w; } } }
	s_nop 0
	v_mov_b32_e32 v56, v212
	v_mov_b32_e32 v57, v213
	v_mov_b32_e32 v58, v214
	v_mov_b32_e32 v59, v215
	ds_read2st64_b32 v[60:61], v144 offset1:1
	ds_read2st64_b32 v[62:63], v144 offset0:2 offset1:3
	ds_read2st64_b32 v[174:175], v144 offset0:4 offset1:5
	ds_read2st64_b32 v[176:177], v144 offset0:6 offset1:7
	v_lshlrev_b32_e32 v180, 16, v100
	s_waitcnt lgkmcnt(3)
	v_add_f32_e32 v60, 0, v60
	v_add_f32_e32 v60, v60, v61
	s_waitcnt lgkmcnt(2)
	v_add_f32_e32 v60, v60, v62
	v_add_f32_e32 v60, v60, v63
	s_waitcnt lgkmcnt(1)
	v_add_f32_e32 v60, v60, v174
	v_add_f32_e32 v60, v60, v175
	s_waitcnt lgkmcnt(0)
	v_add_f32_e32 v60, v60, v176
	v_add_f32_e32 v60, v60, v177
	v_lshlrev_b32_e32 v182, 16, v101
	v_fmamk_f32 v60, v60, 0x3b800000, v169
	v_and_b32_e32 v100, 0xffff0000, v100
	v_and_b32_e32 v184, 0xffff0000, v101
	v_mul_f32_e32 v64, 0xbfb8aa3b, v180
	v_mul_f32_e32 v173, 0xbfb8aa3b, v182
	v_mul_f32_e32 v62, 0x4b800000, v60
	v_cmp_gt_f32_e32 vcc, s90, v60
	v_add_u32_e32 v178, s60, v132
	v_mul_f32_e32 v101, 0xbfb8aa3b, v100
	v_mul_f32_e32 v181, 0xbfb8aa3b, v184
	v_exp_f32_e32 v64, v64
	v_exp_f32_e32 v173, v173
	v_cndmask_b32_e32 v60, v60, v62, vcc
	v_ashrrev_i32_e32 v179, 31, v178
	v_exp_f32_e32 v101, v101
	v_exp_f32_e32 v181, v181
	v_rsq_f32_e32 v63, v60
	v_lshlrev_b64 v[178:179], 11, v[178:179]
	v_lshl_add_u64 v[178:179], s[62:63], 0, v[178:179]
	v_lshl_add_u64 v[178:179], v[178:179], 0, v[88:89]
	v_add_f32_e32 v61, 1.0, v64
	v_add_f32_e32 v89, 1.0, v173
	v_add_f32_e32 v64, 1.0, v101
	v_add_f32_e32 v173, 1.0, v181
	v_rcp_f32_e32 v60, v61
	v_rcp_f32_e32 v62, v89
	v_mul_f32_e32 v61, 0x45800000, v63
	v_cndmask_b32_e32 v89, v63, v61, vcc
	v_mul_f32_e32 v181, v52, v89
	v_mul_f32_e32 v183, v54, v89
	v_mul_f32_e32 v101, v53, v89
	v_mul_f32_e32 v185, v55, v89
	s_nop 0
	v_mov_b32_e32 v61, v56
	v_rcp_f32_e32 v56, v64
	v_mov_b32_e32 v63, v58
	v_rcp_f32_e32 v58, v173
	v_pk_mul_f32 v[52:53], v[60:61], v[180:181]
	v_pk_mul_f32 v[54:55], v[62:63], v[182:183]
	v_mul_f32_e32 v60, v52, v53
	v_mul_f32_e32 v61, v54, v55
	v_pk_mul_f32 v[52:53], v[56:57], v[100:101]
	v_pk_mul_f32 v[54:55], v[58:59], v[184:185]
	v_mul_f32_e32 v52, v52, v53
	v_mul_f32_e32 v53, v54, v55
	v_cvt_pk_bf16_f32 v52, v60, v52
	v_cvt_pk_bf16_f32 v53, v61, v53
	global_store_dwordx2 v[178:179], v[52:53], off
	s_nop 0
	v_mov_b32_e32 v52, v216
	v_mov_b32_e32 v53, v217
	v_mov_b32_e32 v54, v218
	v_mov_b32_e32 v55, v219
	v_lshlrev_b32_e32 v56, 16, v98
	v_and_b32_e32 v58, 0xffff0000, v98
	v_lshlrev_b32_e32 v60, 16, v99
	v_and_b32_e32 v62, 0xffff0000, v99
	v_mul_f32_e32 v57, 0xbfb8aa3b, v56
	v_mul_f32_e32 v59, 0xbfb8aa3b, v58
	v_mul_f32_e32 v61, 0xbfb8aa3b, v60
	v_mul_f32_e32 v63, 0xbfb8aa3b, v62
	v_exp_f32_e32 v57, v57
	v_exp_f32_e32 v59, v59
	v_exp_f32_e32 v61, v61
	v_exp_f32_e32 v63, v63
	v_add_f32_e32 v57, 1.0, v57
	v_add_f32_e32 v64, 1.0, v59
	v_add_f32_e32 v59, 1.0, v61
	v_add_f32_e32 v173, 1.0, v63
	v_rcp_f32_e32 v98, v57
	v_rcp_f32_e32 v100, v59
	v_mul_f32_e32 v57, v48, v89
	v_mul_f32_e32 v61, v50, v89
	v_mul_f32_e32 v59, v49, v89
	v_mul_f32_e32 v63, v51, v89
	s_nop 0
	v_mov_b32_e32 v99, v52
	v_rcp_f32_e32 v52, v64
	v_mov_b32_e32 v101, v54
	v_rcp_f32_e32 v54, v173
	v_pk_mul_f32 v[48:49], v[98:99], v[56:57]
	v_pk_mul_f32 v[50:51], v[100:101], v[60:61]
	v_mul_f32_e32 v56, v48, v49
	v_mul_f32_e32 v57, v50, v51
	v_pk_mul_f32 v[48:49], v[52:53], v[58:59]
	v_pk_mul_f32 v[50:51], v[54:55], v[62:63]
	v_mul_f32_e32 v48, v48, v49
	v_mul_f32_e32 v49, v50, v51
	v_cvt_pk_bf16_f32 v48, v56, v48
	v_cvt_pk_bf16_f32 v49, v57, v49
	global_store_dwordx2 v[178:179], v[48:49], off offset:32
	s_or_b64 exec, exec, s[76:77]
	v_cmp_gt_u32_e32 vcc, s95, v133
	s_and_saveexec_b64 s[76:77], vcc
	s_cbranch_execnz .LBB0_2178

; __device__ __forceinline__ void gla_g3(const Params& P, unsigned char* lds) {
;     ...
;         for (int s = 0; s < 2; ++s) { const int t8 = 32 * s + 8 * fq;
;             if (32 * s < I.L) {
;                 bf16x8 vf[2];
; #pragma unroll
;                 for (int nt = 0; nt < 2; ++nt) { const int tc = t8 < I.L ? t8 : 0; vf[nt] = *(const bf16x8*)(vT + (size_t)(I.h * DV + 32 * wid + 16 * nt + fr) * MPAD + I.row0 + tc); if (t8 >= I.L) vf[nt] = (bf16x8){0, 0, 0, 0, 0, 0, 0, 0}; }
;     ...
;         u32x2 gwp[4][2];
; #pragma unroll
;         for (int lt = 0; lt < 4; ++lt)
; #pragma unroll
;             for (int nt = 0; nt < 2; ++nt) { const int l = 16 * lt + fr, lc = l < I.L ? l : I.L - 1;
;                 gwp[lt][nt] = *(const u32x2*)(gg + (size_t)(I.row0 + lc) * D + I.h * DV + 32 * wid + 16 * nt + 4 * fq); }
.Lg3_loadb:
	s_and_b32 s49, s46, 3
	s_lshl_b32 s46, s49, 8
	s_lshl_b32 s98, s49, 9
	s_add_u32 s100, s54, 0x308dc00
	s_addc_u32 s101, s55, 0
	v_lshrrev_b32_e32 v48, 3, v210
	v_add_u32_e32 v48, s60, v48
	v_lshlrev_b32_e32 v48, 11, v48
	v_and_b32_e32 v49, 7, v210
	v_lshl_add_u32 v49, v49, 6, s98
	v_add_u32_e32 v48, v48, v49
	v_lshlrev_b32_e32 v49, 6, v210
	v_add_u32_e32 v49, 0x1000, v49
	v_lshlrev_b32_e64 v220, 1, s60
	v_add_u32_e32 v223, s46, v128
	v_mul_u32_u24_e32 v223, 0x8280, v223
	v_cmp_gt_u32_e32 vcc, s95, v70
	s_nop 1
	v_cndmask_b32_e32 v222, 0, v70, vcc
	v_lshl_add_u32 v222, v222, 1, v220
	v_add_u32_e32 v222, v222, v223
	v_mov_b32_e32 v225, s78
	v_add_co_u32_e32 v224, vcc, s3, v222
	v_addc_co_u32_e32 v225, vcc, 0, v225, vcc
	global_load_dwordx4 v[194:197], v[224:225], off
	v_add_co_u32_e32 v226, vcc, 0x82800, v224
	v_addc_co_u32_e32 v227, vcc, 0, v225, vcc
	global_load_dwordx4 v[198:201], v[226:227], off
	v_cmp_gt_u32_e32 vcc, s95, v135
	s_nop 1
	v_cndmask_b32_e32 v222, 0, v135, vcc
	v_lshl_add_u32 v222, v222, 1, v220
	v_add_u32_e32 v222, v222, v223
	v_mov_b32_e32 v225, s78
	v_add_co_u32_e32 v224, vcc, s3, v222
	v_addc_co_u32_e32 v225, vcc, 0, v225, vcc
	global_load_dwordx4 v[202:205], v[224:225], off
	v_add_co_u32_e32 v226, vcc, 0x82800, v224
	v_addc_co_u32_e32 v227, vcc, 0, v225, vcc
	global_load_dwordx4 v[206:209], v[226:227], off
	s_add_i32 s98, s95, -1
	s_lshl_b32 s99, s46, 1
	v_min_i32_e32 v220, s98, v103
	v_add_u32_e32 v220, s60, v220
	v_lshlrev_b32_e32 v220, 11, v220
	v_add_u32_e32 v220, s99, v220
	v_add_co_u32_e32 v222, vcc, v74, v220
	v_addc_co_u32_e32 v223, vcc, 0, v75, vcc
	global_load_dwordx2 v[228:229], v[222:223], off
	global_load_dwordx2 v[230:231], v[222:223], off offset:32
	v_min_i32_e32 v220, s98, v132
	v_add_u32_e32 v220, s60, v220
	v_lshlrev_b32_e32 v220, 11, v220
	v_add_u32_e32 v220, s99, v220
	v_add_co_u32_e32 v222, vcc, v74, v220
	v_addc_co_u32_e32 v223, vcc, 0, v75, vcc
	global_load_dwordx2 v[232:233], v[222:223], off
	global_load_dwordx2 v[234:235], v[222:223], off offset:32
	v_min_i32_e32 v220, s98, v133
	v_add_u32_e32 v220, s60, v220
	v_lshlrev_b32_e32 v220, 11, v220
	v_add_u32_e32 v220, s99, v220
	v_add_co_u32_e32 v222, vcc, v74, v220
	v_addc_co_u32_e32 v223, vcc, 0, v75, vcc
	global_load_dwordx2 v[236:237], v[222:223], off
	global_load_dwordx2 v[238:239], v[222:223], off offset:32
	v_min_i32_e32 v220, s98, v134
	v_add_u32_e32 v220, s60, v220
	v_lshlrev_b32_e32 v220, 11, v220
	v_add_u32_e32 v220, s99, v220
	v_add_co_u32_e32 v222, vcc, v74, v220
	v_addc_co_u32_e32 v223, vcc, 0, v75, vcc
	global_load_dwordx2 v[244:245], v[222:223], off
	global_load_dwordx2 v[246:247], v[222:223], off offset:32
	s_mov_b64 s[98:99], exec
	s_cmp_eq_u32 s95, 64
	s_cbranch_scc1 .Lg3_ball
	v_cmp_gt_u32_e32 vcc, 0x80, v210
	s_nop 1
	s_and_b64 exec, exec, vcc
	s_cbranch_execz .Lg3_bskip
